# GEMM K-loops: s_setprio 1 moved before the second barrier so fragment reads issue immediately after it
# baseline (speedup 1.0000x reference)
; template <bool DEEP, class Epi>
; __device__ __forceinline__ void gemm_phase(const bf16_t* __restrict__ A, int lda, const bf16_t* __restrict__ Wt,
;                                            int K, int ntn, bool lat_only, const Epi& epi, char* smem) {
;     ...
;     for (int kt = 0; kt < nk; ++kt) {
;       __syncthreads();
;       GEMM_STORE(ra0, ra1, ra2, ra3, rb0, rb1, rb2, rb3, 0)
;       __syncthreads();
;       {
;         bf16x8 af0[4], bf0[4], af1[4], bf1[4];
;         __builtin_amdgcn_s_setprio(1);
; #pragma unroll
;         for (int i = 0; i < 4; ++i) af0[i] = *(const bf16x8*)(sA + (wm * 64 + i * 16 + l15) * LSTR + quad * 8);
; #pragma unroll
;         for (int j = 0; j < 4; ++j) bf0[j] = *(const bf16x8*)(sB + (wn * 64 + j * 16 + l15) * LSTR + quad * 8);
; #pragma unroll
;         for (int i = 0; i < 4; ++i) af1[i] = *(const bf16x8*)(sA + (wm * 64 + i * 16 + l15) * LSTR + 32 + quad * 8);
; #pragma unroll
;         for (int j = 0; j < 4; ++j) bf1[j] = *(const bf16x8*)(sB + (wn * 64 + j * 16 + l15) * LSTR + 32 + quad * 8);
;         __builtin_amdgcn_sched_barrier(0);
;         if (kt + 1 < nk) GEMM_LOAD(ra0, ra1, ra2, ra3, rb0, rb1, rb2, rb3, (kt + 1) * 64)
.LBB0_140:
	s_barrier
	s_waitcnt vmcnt(7)
	ds_write_b128 v165, v[64:67]
	s_waitcnt vmcnt(6)
	ds_write_b128 v165, v[68:71] offset:5120
	s_waitcnt vmcnt(5)
	ds_write_b128 v165, v[72:75] offset:10240
	s_waitcnt vmcnt(4)
	ds_write_b128 v165, v[76:79] offset:15360
	s_waitcnt vmcnt(3)
	ds_write_b128 v165, v[80:83] offset:20480
	s_waitcnt vmcnt(2)
	ds_write_b128 v165, v[84:87] offset:25600
	s_waitcnt vmcnt(1)
	ds_write_b128 v165, v[88:91] offset:30720
	s_waitcnt vmcnt(0)
	ds_write_b128 v165, v[92:95] offset:35840
	v_add_u32_e32 v96, v173, v175
	s_setprio 1
	s_waitcnt lgkmcnt(0)
	s_barrier
	ds_read_b128 v[156:159], v96
	ds_read_b128 v[152:155], v96 offset:2560
	ds_read_b128 v[132:135], v96 offset:5120
	ds_read_b128 v[124:127], v96 offset:7680
	ds_read_b128 v[136:139], v181 offset:20480
	ds_read_b128 v[140:143], v181 offset:23040
	ds_read_b128 v[144:147], v181 offset:25600
	ds_read_b128 v[148:151], v181 offset:28160
	ds_read_b128 v[128:131], v183 offset:64
	ds_read_b128 v[120:123], v183 offset:2624
	ds_read_b128 v[100:103], v183 offset:5184
	ds_read_b128 v[96:99], v183 offset:7744
	ds_read_b128 v[104:107], v185 offset:20544
	ds_read_b128 v[108:111], v185 offset:23104
	ds_read_b128 v[112:115], v185 offset:25664
	ds_read_b128 v[116:119], v185 offset:28224
	s_cmpk_eq_i32 s0, 0x780
	s_cbranch_scc1 .LBB0_139
	v_lshl_add_u64 v[72:73], v[238:239], 0, s[0:1]
	v_add_co_u32_e32 v64, vcc, 0x1d00000, v72
	v_lshl_add_u64 v[88:89], v[240:241], 0, s[0:1]
	s_nop 0
	v_addc_co_u32_e32 v65, vcc, 0, v73, vcc
	v_add_co_u32_e32 v68, vcc, 0x1d10000, v72
	s_nop 1
	v_addc_co_u32_e32 v69, vcc, 0, v73, vcc
	v_add_co_u32_e32 v74, vcc, 0x1d20000, v72
	global_load_dwordx4 v[64:67], v[64:65], off offset:128
	s_nop 0
	global_load_dwordx4 v[68:71], v[68:69], off offset:128
	v_addc_co_u32_e32 v75, vcc, 0, v73, vcc
	v_add_co_u32_e32 v76, vcc, 0x1d30000, v72
	s_nop 1
	v_addc_co_u32_e32 v77, vcc, 0, v73, vcc
	v_add_co_u32_e32 v84, vcc, 0x10000, v88
	global_load_dwordx4 v[72:75], v[74:75], off offset:128
	s_nop 0
	global_load_dwordx4 v[76:79], v[76:77], off offset:128
	v_addc_co_u32_e32 v85, vcc, 0, v89, vcc
	v_add_co_u32_e32 v90, vcc, 0x20000, v88
	global_load_dwordx4 v[80:83], v[88:89], off offset:128
	s_nop 0
	global_load_dwordx4 v[84:87], v[84:85], off offset:128
	v_addc_co_u32_e32 v91, vcc, 0, v89, vcc
	v_add_co_u32_e32 v92, vcc, 0x30000, v88
	s_nop 1
	v_addc_co_u32_e32 v93, vcc, 0, v89, vcc
	global_load_dwordx4 v[88:91], v[90:91], off offset:128
	s_nop 0
	global_load_dwordx4 v[92:95], v[92:93], off offset:128
	s_branch .LBB0_139

; template <bool DEEP, class Epi>
; __device__ __forceinline__ void gemm_phase(const bf16_t* __restrict__ A, int lda, const bf16_t* __restrict__ Wt,
;                                            int K, int ntn, bool lat_only, const Epi& epi, char* smem) {
;     ...
;     for (int kt = 0; kt < nk; ++kt) {
;       __syncthreads();
;       GEMM_STORE(ra0, ra1, ra2, ra3, rb0, rb1, rb2, rb3, 0)
;       __syncthreads();
;       {
;         bf16x8 af0[4], bf0[4], af1[4], bf1[4];
;         __builtin_amdgcn_s_setprio(1);
; #pragma unroll
;         for (int i = 0; i < 4; ++i) af0[i] = *(const bf16x8*)(sA + (wm * 64 + i * 16 + l15) * LSTR + quad * 8);
; #pragma unroll
;         for (int j = 0; j < 4; ++j) bf0[j] = *(const bf16x8*)(sB + (wn * 64 + j * 16 + l15) * LSTR + quad * 8);
; #pragma unroll
;         for (int i = 0; i < 4; ++i) af1[i] = *(const bf16x8*)(sA + (wm * 64 + i * 16 + l15) * LSTR + 32 + quad * 8);
; #pragma unroll
;         for (int j = 0; j < 4; ++j) bf1[j] = *(const bf16x8*)(sB + (wn * 64 + j * 16 + l15) * LSTR + 32 + quad * 8);
;         __builtin_amdgcn_sched_barrier(0);
;         if (kt + 1 < nk) GEMM_LOAD(ra0, ra1, ra2, ra3, rb0, rb1, rb2, rb3, (kt + 1) * 64)
.LBB0_438:
	s_waitcnt vmcnt(63) expcnt(7) lgkmcnt(15)
	s_barrier
	s_waitcnt vmcnt(0)
	ds_write_b128 v161, v[64:67]
	ds_write_b128 v161, v[68:71] offset:5120
	ds_write_b128 v161, v[80:83] offset:10240
	ds_write_b128 v161, v[88:91] offset:15360
	ds_write_b128 v161, v[72:75] offset:20480
	ds_write_b128 v161, v[76:79] offset:25600
	ds_write_b128 v161, v[84:87] offset:30720
	ds_write_b128 v161, v[92:95] offset:35840
	v_add_u32_e32 v96, v175, v178
	s_setprio 1
	s_waitcnt lgkmcnt(0)
	s_barrier
	ds_read_b128 v[156:159], v96
	ds_read_b128 v[152:155], v96 offset:2560
	ds_read_b128 v[132:135], v96 offset:5120
	ds_read_b128 v[124:127], v96 offset:7680
	ds_read_b128 v[136:139], v180 offset:20480
	ds_read_b128 v[140:143], v180 offset:23040
	ds_read_b128 v[144:147], v180 offset:25600
	ds_read_b128 v[148:151], v180 offset:28160
	ds_read_b128 v[128:131], v182 offset:64
	ds_read_b128 v[120:123], v182 offset:2624
	ds_read_b128 v[100:103], v182 offset:5184
	ds_read_b128 v[96:99], v182 offset:7744
	ds_read_b128 v[104:107], v183 offset:20544
	ds_read_b128 v[108:111], v183 offset:23104
	ds_read_b128 v[112:115], v183 offset:25664
	ds_read_b128 v[116:119], v183 offset:28224
	s_cmp_gt_u32 s1, 14
	s_cbranch_scc1 .LBB0_437
	v_lshl_add_u64 v[72:73], v[170:171], 0, s[12:13]
	v_add_co_u32_e32 v64, vcc, 0x1d00000, v72
	v_lshl_add_u64 v[84:85], v[172:173], 0, s[12:13]
	s_nop 0
	v_addc_co_u32_e32 v65, vcc, 0, v73, vcc
	v_add_co_u32_e32 v68, vcc, 0x1d10000, v72
	s_nop 1
	v_addc_co_u32_e32 v69, vcc, 0, v73, vcc
	v_add_co_u32_e32 v74, vcc, 0x1d20000, v72
	global_load_dwordx4 v[64:67], v[64:65], off offset:128
	s_nop 0
	global_load_dwordx4 v[68:71], v[68:69], off offset:128
	v_addc_co_u32_e32 v75, vcc, 0, v73, vcc
	v_add_co_u32_e32 v72, vcc, 0x1d30000, v72
	s_nop 1
	v_addc_co_u32_e32 v73, vcc, 0, v73, vcc
	global_load_dwordx4 v[80:83], v[74:75], off offset:128
	global_load_dwordx4 v[88:91], v[72:73], off offset:128
	v_add_co_u32_e32 v72, vcc, 0x680000, v84
	s_nop 1
	v_addc_co_u32_e32 v73, vcc, 0, v85, vcc
	v_add_co_u32_e32 v76, vcc, 0x690000, v84
	s_nop 1
	v_addc_co_u32_e32 v77, vcc, 0, v85, vcc
	v_add_co_u32_e32 v86, vcc, 0x6a0000, v84
	global_load_dwordx4 v[72:75], v[72:73], off offset:128
	s_nop 0
	global_load_dwordx4 v[76:79], v[76:77], off offset:128
	v_addc_co_u32_e32 v87, vcc, 0, v85, vcc
	v_add_co_u32_e32 v92, vcc, 0x6b0000, v84
	s_nop 1
	v_addc_co_u32_e32 v93, vcc, 0, v85, vcc
	global_load_dwordx4 v[84:87], v[86:87], off offset:128
	s_nop 0
	global_load_dwordx4 v[92:95], v[92:93], off offset:128
	s_branch .LBB0_437

; template <bool DEEP, class Epi>
; __device__ __forceinline__ void gemm_phase(const bf16_t* __restrict__ A, int lda, const bf16_t* __restrict__ Wt,
;                                            int K, int ntn, bool lat_only, const Epi& epi, char* smem) {
;     ...
;     for (int kt = 0; kt < nk; ++kt) {
;       __syncthreads();
;       GEMM_STORE(ra0, ra1, ra2, ra3, rb0, rb1, rb2, rb3, 0)
;       __syncthreads();
;       {
;         bf16x8 af0[4], bf0[4], af1[4], bf1[4];
;         __builtin_amdgcn_s_setprio(1);
; #pragma unroll
;         for (int i = 0; i < 4; ++i) af0[i] = *(const bf16x8*)(sA + (wm * 64 + i * 16 + l15) * LSTR + quad * 8);
; #pragma unroll
;         for (int j = 0; j < 4; ++j) bf0[j] = *(const bf16x8*)(sB + (wn * 64 + j * 16 + l15) * LSTR + quad * 8);
; #pragma unroll
;         for (int i = 0; i < 4; ++i) af1[i] = *(const bf16x8*)(sA + (wm * 64 + i * 16 + l15) * LSTR + 32 + quad * 8);
; #pragma unroll
;         for (int j = 0; j < 4; ++j) bf1[j] = *(const bf16x8*)(sB + (wn * 64 + j * 16 + l15) * LSTR + 32 + quad * 8);
;         __builtin_amdgcn_sched_barrier(0);
;         if (kt + 1 < nk) GEMM_LOAD(ra0, ra1, ra2, ra3, rb0, rb1, rb2, rb3, (kt + 1) * 64)
.LBB0_576:
	s_waitcnt vmcnt(63) expcnt(7) lgkmcnt(15)
	s_barrier
	s_waitcnt vmcnt(7)
	ds_write_b128 v176, v[56:59]
	s_waitcnt vmcnt(6)
	ds_write_b128 v176, v[60:63] offset:5120
	s_waitcnt vmcnt(5)
	ds_write_b128 v176, v[68:71] offset:10240
	s_waitcnt vmcnt(4)
	ds_write_b128 v176, v[76:79] offset:15360
	s_waitcnt vmcnt(3)
	ds_write_b128 v176, v[80:83] offset:20480
	s_waitcnt vmcnt(2)
	ds_write_b128 v176, v[84:87] offset:25600
	s_waitcnt vmcnt(1)
	ds_write_b128 v176, v[88:91] offset:30720
	s_waitcnt vmcnt(0)
	ds_write_b128 v176, v[92:95] offset:35840
	v_add_u32_e32 v96, v180, v182
	s_setprio 1
	s_waitcnt lgkmcnt(0)
	s_barrier
	ds_read_b128 v[156:159], v96
	ds_read_b128 v[152:155], v96 offset:2560
	ds_read_b128 v[132:135], v96 offset:5120
	ds_read_b128 v[124:127], v96 offset:7680
	ds_read_b128 v[136:139], v183 offset:20480
	ds_read_b128 v[140:143], v183 offset:23040
	ds_read_b128 v[144:147], v183 offset:25600
	ds_read_b128 v[148:151], v183 offset:28160
	ds_read_b128 v[128:131], v184 offset:64
	ds_read_b128 v[120:123], v184 offset:2624
	ds_read_b128 v[100:103], v184 offset:5184
	ds_read_b128 v[96:99], v184 offset:7744
	ds_read_b128 v[104:107], v185 offset:20544
	ds_read_b128 v[108:111], v185 offset:23104
	ds_read_b128 v[112:115], v185 offset:25664
	ds_read_b128 v[116:119], v185 offset:28224
	s_cmpk_eq_i32 s8, 0x780
	s_cbranch_scc1 .LBB0_575
	v_lshl_add_u64 v[68:69], v[172:173], 0, s[8:9]
	v_add_co_u32_e32 v56, vcc, 0x1d00000, v68
	v_lshl_add_u64 v[88:89], v[174:175], 0, s[8:9]
	s_nop 0
	v_addc_co_u32_e32 v57, vcc, 0, v69, vcc
	v_add_co_u32_e32 v60, vcc, 0x1d10000, v68
	s_nop 1
	v_addc_co_u32_e32 v61, vcc, 0, v69, vcc
	v_add_co_u32_e32 v70, vcc, 0x1d20000, v68
	global_load_dwordx4 v[56:59], v[56:57], off offset:128
	s_nop 0
	global_load_dwordx4 v[60:63], v[60:61], off offset:128
	v_addc_co_u32_e32 v71, vcc, 0, v69, vcc
	v_add_co_u32_e32 v76, vcc, 0x1d30000, v68
	s_nop 1
	v_addc_co_u32_e32 v77, vcc, 0, v69, vcc
	v_add_co_u32_e32 v80, vcc, 0x880000, v88
	global_load_dwordx4 v[68:71], v[70:71], off offset:128
	s_nop 0
	global_load_dwordx4 v[76:79], v[76:77], off offset:128
	v_addc_co_u32_e32 v81, vcc, 0, v89, vcc
	v_add_co_u32_e32 v84, vcc, 0x890000, v88
	s_nop 1
	v_addc_co_u32_e32 v85, vcc, 0, v89, vcc
	v_add_co_u32_e32 v90, vcc, 0x8a0000, v88
	global_load_dwordx4 v[80:83], v[80:81], off offset:128
	s_nop 0
	global_load_dwordx4 v[84:87], v[84:85], off offset:128
	v_addc_co_u32_e32 v91, vcc, 0, v89, vcc
	v_add_co_u32_e32 v92, vcc, 0x8b0000, v88
	s_nop 1
	v_addc_co_u32_e32 v93, vcc, 0, v89, vcc
	global_load_dwordx4 v[88:91], v[90:91], off offset:128
	s_nop 0
	global_load_dwordx4 v[92:95], v[92:93], off offset:128
	s_branch .LBB0_575

; template <bool DEEP, class Epi>
; __device__ __forceinline__ void gemm_phase(const bf16_t* __restrict__ A, int lda, const bf16_t* __restrict__ Wt,
;                                            int K, int ntn, bool lat_only, const Epi& epi, char* smem) {
;     ...
;     for (int kt = 0; kt < nk; ++kt) {
;       __syncthreads();
;       GEMM_STORE(ra0, ra1, ra2, ra3, rb0, rb1, rb2, rb3, 0)
;       __syncthreads();
;       {
;         bf16x8 af0[4], bf0[4], af1[4], bf1[4];
;         __builtin_amdgcn_s_setprio(1);
; #pragma unroll
;         for (int i = 0; i < 4; ++i) af0[i] = *(const bf16x8*)(sA + (wm * 64 + i * 16 + l15) * LSTR + quad * 8);
; #pragma unroll
;         for (int j = 0; j < 4; ++j) bf0[j] = *(const bf16x8*)(sB + (wn * 64 + j * 16 + l15) * LSTR + quad * 8);
; #pragma unroll
;         for (int i = 0; i < 4; ++i) af1[i] = *(const bf16x8*)(sA + (wm * 64 + i * 16 + l15) * LSTR + 32 + quad * 8);
; #pragma unroll
;         for (int j = 0; j < 4; ++j) bf1[j] = *(const bf16x8*)(sB + (wn * 64 + j * 16 + l15) * LSTR + 32 + quad * 8);
;         __builtin_amdgcn_sched_barrier(0);
;         if (kt + 1 < nk) GEMM_LOAD(ra0, ra1, ra2, ra3, rb0, rb1, rb2, rb3, (kt + 1) * 64)
.LBB0_635:
	s_waitcnt vmcnt(63) expcnt(7) lgkmcnt(15)
	s_barrier
	s_waitcnt vmcnt(0)
	ds_write_b128 v161, v[64:67]
	ds_write_b128 v161, v[68:71] offset:5120
	ds_write_b128 v161, v[80:83] offset:10240
	ds_write_b128 v161, v[88:91] offset:15360
	ds_write_b128 v161, v[72:75] offset:20480
	ds_write_b128 v161, v[76:79] offset:25600
	ds_write_b128 v161, v[84:87] offset:30720
	ds_write_b128 v161, v[92:95] offset:35840
	v_add_u32_e32 v96, v175, v178
	s_setprio 1
	s_waitcnt lgkmcnt(0)
	s_barrier
	ds_read_b128 v[156:159], v96
	ds_read_b128 v[152:155], v96 offset:2560
	ds_read_b128 v[132:135], v96 offset:5120
	ds_read_b128 v[124:127], v96 offset:7680
	ds_read_b128 v[136:139], v182 offset:20480
	ds_read_b128 v[140:143], v182 offset:23040
	ds_read_b128 v[144:147], v182 offset:25600
	ds_read_b128 v[148:151], v182 offset:28160
	ds_read_b128 v[128:131], v183 offset:64
	ds_read_b128 v[120:123], v183 offset:2624
	ds_read_b128 v[100:103], v183 offset:5184
	ds_read_b128 v[96:99], v183 offset:7744
	ds_read_b128 v[104:107], v184 offset:20544
	ds_read_b128 v[108:111], v184 offset:23104
	ds_read_b128 v[112:115], v184 offset:25664
	ds_read_b128 v[116:119], v184 offset:28224
	s_cmp_gt_u32 s15, 42
	s_cbranch_scc1 .LBB0_634
	v_lshl_add_u64 v[72:73], v[170:171], 0, s[0:1]
	v_add_co_u32_e32 v64, vcc, 0x5e00000, v72
	v_lshl_add_u64 v[84:85], v[172:173], 0, s[0:1]
	s_nop 0
	v_addc_co_u32_e32 v65, vcc, 0, v73, vcc
	v_add_co_u32_e32 v68, vcc, 0x5e2c000, v72
	s_nop 1
	v_addc_co_u32_e32 v69, vcc, 0, v73, vcc
	v_add_co_u32_e32 v74, vcc, 0x5e58000, v72
	global_load_dwordx4 v[64:67], v[64:65], off offset:128
	s_nop 0
	global_load_dwordx4 v[68:71], v[68:69], off offset:128
	v_addc_co_u32_e32 v75, vcc, 0, v73, vcc
	v_add_co_u32_e32 v72, vcc, 0x5e84000, v72
	s_nop 1
	v_addc_co_u32_e32 v73, vcc, 0, v73, vcc
	global_load_dwordx4 v[80:83], v[74:75], off offset:128
	global_load_dwordx4 v[88:91], v[72:73], off offset:128
	v_add_co_u32_e32 v72, vcc, 0x1380000, v84
	s_nop 1
	v_addc_co_u32_e32 v73, vcc, 0, v85, vcc
	v_add_co_u32_e32 v76, vcc, 0x13ac000, v84
	s_nop 1
	v_addc_co_u32_e32 v77, vcc, 0, v85, vcc
	v_add_co_u32_e32 v86, vcc, 0x13d8000, v84
	global_load_dwordx4 v[72:75], v[72:73], off offset:128
	s_nop 0
	global_load_dwordx4 v[76:79], v[76:77], off offset:128
	v_addc_co_u32_e32 v87, vcc, 0, v85, vcc
	v_add_co_u32_e32 v92, vcc, 0x1404000, v84
	s_nop 1
	v_addc_co_u32_e32 v93, vcc, 0, v85, vcc
	global_load_dwordx4 v[84:87], v[86:87], off offset:128
	s_nop 0
	global_load_dwordx4 v[92:95], v[92:93], off offset:128
	s_branch .LBB0_634

; template <bool DEEP, class Epi>
; __device__ __forceinline__ void gemm_phase(const bf16_t* __restrict__ A, int lda, const bf16_t* __restrict__ Wt,
;                                            int K, int ntn, bool lat_only, const Epi& epi, char* smem) {
;     ...
;     for (int kt = 0; kt < nk; ++kt) {
;       __syncthreads();
;       GEMM_STORE(ra0, ra1, ra2, ra3, rb0, rb1, rb2, rb3, 0)
;       __syncthreads();
;       {
;         bf16x8 af0[4], bf0[4], af1[4], bf1[4];
;         __builtin_amdgcn_s_setprio(1);
; #pragma unroll
;         for (int i = 0; i < 4; ++i) af0[i] = *(const bf16x8*)(sA + (wm * 64 + i * 16 + l15) * LSTR + quad * 8);
; #pragma unroll
;         for (int j = 0; j < 4; ++j) bf0[j] = *(const bf16x8*)(sB + (wn * 64 + j * 16 + l15) * LSTR + quad * 8);
; #pragma unroll
;         for (int i = 0; i < 4; ++i) af1[i] = *(const bf16x8*)(sA + (wm * 64 + i * 16 + l15) * LSTR + 32 + quad * 8);
; #pragma unroll
;         for (int j = 0; j < 4; ++j) bf1[j] = *(const bf16x8*)(sB + (wn * 64 + j * 16 + l15) * LSTR + 32 + quad * 8);
;         __builtin_amdgcn_sched_barrier(0);
;         if (kt + 1 < nk) GEMM_LOAD(ra0, ra1, ra2, ra3, rb0, rb1, rb2, rb3, (kt + 1) * 64)
.LBB0_848:
	s_waitcnt vmcnt(63) expcnt(7) lgkmcnt(15)
	s_barrier
	s_waitcnt vmcnt(7)
	ds_write_b128 v173, v[64:67]
	s_waitcnt vmcnt(6)
	ds_write_b128 v173, v[68:71] offset:5120
	s_waitcnt vmcnt(5)
	ds_write_b128 v173, v[72:75] offset:10240
	s_waitcnt vmcnt(4)
	ds_write_b128 v173, v[76:79] offset:15360
	s_waitcnt vmcnt(3)
	ds_write_b128 v173, v[80:83] offset:20480
	s_waitcnt vmcnt(2)
	ds_write_b128 v173, v[84:87] offset:25600
	s_waitcnt vmcnt(1)
	ds_write_b128 v173, v[88:91] offset:30720
	s_waitcnt vmcnt(0)
	ds_write_b128 v173, v[92:95] offset:35840
	v_add_u32_e32 v96, v183, v187
	s_setprio 1
	s_waitcnt lgkmcnt(0)
	s_barrier
	ds_read_b128 v[156:159], v96
	ds_read_b128 v[152:155], v96 offset:2560
	ds_read_b128 v[132:135], v96 offset:5120
	ds_read_b128 v[124:127], v96 offset:7680
	ds_read_b128 v[136:139], v189 offset:20480
	ds_read_b128 v[140:143], v189 offset:23040
	ds_read_b128 v[144:147], v189 offset:25600
	ds_read_b128 v[148:151], v189 offset:28160
	ds_read_b128 v[128:131], v191 offset:64
	ds_read_b128 v[120:123], v191 offset:2624
	ds_read_b128 v[100:103], v191 offset:5184
	ds_read_b128 v[96:99], v191 offset:7744
	ds_read_b128 v[104:107], v193 offset:20544
	ds_read_b128 v[108:111], v193 offset:23104
	ds_read_b128 v[112:115], v193 offset:25664
	ds_read_b128 v[116:119], v193 offset:28224
	s_cmpk_eq_i32 s6, 0x780
	s_cbranch_scc1 .LBB0_847
	v_lshl_add_u64 v[72:73], v[204:205], 0, s[6:7]
	v_add_co_u32_e32 v64, vcc, 0x1d00000, v72
	v_lshl_add_u64 v[88:89], v[206:207], 0, s[6:7]
	s_nop 0
	v_addc_co_u32_e32 v65, vcc, 0, v73, vcc
	v_add_co_u32_e32 v68, vcc, 0x1d10000, v72
	s_nop 1
	v_addc_co_u32_e32 v69, vcc, 0, v73, vcc
	v_add_co_u32_e32 v74, vcc, 0x1d20000, v72
	global_load_dwordx4 v[64:67], v[64:65], off offset:128
	s_nop 0
	global_load_dwordx4 v[68:71], v[68:69], off offset:128
	v_addc_co_u32_e32 v75, vcc, 0, v73, vcc
	v_add_co_u32_e32 v76, vcc, 0x1d30000, v72
	s_nop 1
	v_addc_co_u32_e32 v77, vcc, 0, v73, vcc
	v_add_co_u32_e32 v84, vcc, 0x10000, v88
	global_load_dwordx4 v[72:75], v[74:75], off offset:128
	s_nop 0
	global_load_dwordx4 v[76:79], v[76:77], off offset:128
	v_addc_co_u32_e32 v85, vcc, 0, v89, vcc
	v_add_co_u32_e32 v90, vcc, 0x20000, v88
	global_load_dwordx4 v[80:83], v[88:89], off offset:128
	s_nop 0
	global_load_dwordx4 v[84:87], v[84:85], off offset:128
	v_addc_co_u32_e32 v91, vcc, 0, v89, vcc
	v_add_co_u32_e32 v92, vcc, 0x30000, v88
	s_nop 1
	v_addc_co_u32_e32 v93, vcc, 0, v89, vcc
	global_load_dwordx4 v[88:91], v[90:91], off offset:128
	s_nop 0
	global_load_dwordx4 v[92:95], v[92:93], off offset:128
	s_branch .LBB0_847

; template <bool DEEP, class Epi>
; __device__ __forceinline__ void gemm_phase(const bf16_t* __restrict__ A, int lda, const bf16_t* __restrict__ Wt,
;                                            int K, int ntn, bool lat_only, const Epi& epi, char* smem) {
;     ...
;     for (int kt = 0; kt < nk; ++kt) {
;       __syncthreads();
;       GEMM_STORE(ra0, ra1, ra2, ra3, rb0, rb1, rb2, rb3, 0)
;       __syncthreads();
;       {
;         bf16x8 af0[4], bf0[4], af1[4], bf1[4];
;         __builtin_amdgcn_s_setprio(1);
; #pragma unroll
;         for (int i = 0; i < 4; ++i) af0[i] = *(const bf16x8*)(sA + (wm * 64 + i * 16 + l15) * LSTR + quad * 8);
; #pragma unroll
;         for (int j = 0; j < 4; ++j) bf0[j] = *(const bf16x8*)(sB + (wn * 64 + j * 16 + l15) * LSTR + quad * 8);
; #pragma unroll
;         for (int i = 0; i < 4; ++i) af1[i] = *(const bf16x8*)(sA + (wm * 64 + i * 16 + l15) * LSTR + 32 + quad * 8);
; #pragma unroll
;         for (int j = 0; j < 4; ++j) bf1[j] = *(const bf16x8*)(sB + (wn * 64 + j * 16 + l15) * LSTR + 32 + quad * 8);
;         __builtin_amdgcn_sched_barrier(0);
;         if (kt + 1 < nk) GEMM_LOAD(ra0, ra1, ra2, ra3, rb0, rb1, rb2, rb3, (kt + 1) * 64)
.LBB0_1421:
	s_barrier
	s_waitcnt vmcnt(0)
	ds_write_b128 v161, v[64:67]
	ds_write_b128 v161, v[68:71] offset:5120
	ds_write_b128 v161, v[76:79] offset:10240
	ds_write_b128 v161, v[84:87] offset:15360
	ds_write_b128 v161, v[72:75] offset:20480
	ds_write_b128 v161, v[80:83] offset:25600
	ds_write_b128 v161, v[88:91] offset:30720
	ds_write_b128 v161, v[92:95] offset:35840
	v_add_u32_e32 v96, v173, v175
	s_setprio 1
	s_waitcnt lgkmcnt(0)
	s_barrier
	ds_read_b128 v[156:159], v96
	ds_read_b128 v[152:155], v96 offset:2560
	ds_read_b128 v[132:135], v96 offset:5120
	ds_read_b128 v[124:127], v96 offset:7680
	ds_read_b128 v[136:139], v176 offset:20480
	ds_read_b128 v[140:143], v176 offset:23040
	ds_read_b128 v[144:147], v176 offset:25600
	ds_read_b128 v[148:151], v176 offset:28160
	ds_read_b128 v[128:131], v178 offset:64
	ds_read_b128 v[120:123], v178 offset:2624
	ds_read_b128 v[100:103], v178 offset:5184
	ds_read_b128 v[96:99], v178 offset:7744
	ds_read_b128 v[104:107], v179 offset:20544
	ds_read_b128 v[108:111], v179 offset:23104
	ds_read_b128 v[112:115], v179 offset:25664
	ds_read_b128 v[116:119], v179 offset:28224
	s_cmp_gt_u32 s1, 14
	s_cbranch_scc1 .LBB0_1420
	v_lshl_add_u64 v[72:73], v[168:169], 0, s[8:9]
	v_add_co_u32_e32 v64, vcc, 0x1d00000, v72
	v_lshl_add_u64 v[88:89], v[170:171], 0, s[8:9]
	s_nop 0
	v_addc_co_u32_e32 v65, vcc, 0, v73, vcc
	v_add_co_u32_e32 v68, vcc, 0x1d10000, v72
	s_nop 1
	v_addc_co_u32_e32 v69, vcc, 0, v73, vcc
	v_add_co_u32_e32 v74, vcc, 0x1d20000, v72
	global_load_dwordx4 v[64:67], v[64:65], off offset:128
	s_nop 0
	global_load_dwordx4 v[68:71], v[68:69], off offset:128
	v_addc_co_u32_e32 v75, vcc, 0, v73, vcc
	v_add_co_u32_e32 v72, vcc, 0x1d30000, v72
	s_nop 1
	v_addc_co_u32_e32 v73, vcc, 0, v73, vcc
	global_load_dwordx4 v[76:79], v[74:75], off offset:128
	global_load_dwordx4 v[84:87], v[72:73], off offset:128
	v_add_co_u32_e32 v72, vcc, 0x680000, v88
	s_nop 1
	v_addc_co_u32_e32 v73, vcc, 0, v89, vcc
	v_add_co_u32_e32 v80, vcc, 0x690000, v88
	s_nop 1
	v_addc_co_u32_e32 v81, vcc, 0, v89, vcc
	v_add_co_u32_e32 v90, vcc, 0x6a0000, v88
	global_load_dwordx4 v[72:75], v[72:73], off offset:128
	s_nop 0
	global_load_dwordx4 v[80:83], v[80:81], off offset:128
	v_addc_co_u32_e32 v91, vcc, 0, v89, vcc
	v_add_co_u32_e32 v92, vcc, 0x6b0000, v88
	s_nop 1
	v_addc_co_u32_e32 v93, vcc, 0, v89, vcc
	global_load_dwordx4 v[88:91], v[90:91], off offset:128
	s_nop 0
	global_load_dwordx4 v[92:95], v[92:93], off offset:128
	s_branch .LBB0_1420

; template <bool DEEP, class Epi>
; __device__ __forceinline__ void gemm_phase(const bf16_t* __restrict__ A, int lda, const bf16_t* __restrict__ Wt,
;                                            int K, int ntn, bool lat_only, const Epi& epi, char* smem) {
;     ...
;     for (int kt = 0; kt < nk; ++kt) {
;       __syncthreads();
;       GEMM_STORE(ra0, ra1, ra2, ra3, rb0, rb1, rb2, rb3, 0)
;       __syncthreads();
;       {
;         bf16x8 af0[4], bf0[4], af1[4], bf1[4];
;         __builtin_amdgcn_s_setprio(1);
; #pragma unroll
;         for (int i = 0; i < 4; ++i) af0[i] = *(const bf16x8*)(sA + (wm * 64 + i * 16 + l15) * LSTR + quad * 8);
; #pragma unroll
;         for (int j = 0; j < 4; ++j) bf0[j] = *(const bf16x8*)(sB + (wn * 64 + j * 16 + l15) * LSTR + quad * 8);
; #pragma unroll
;         for (int i = 0; i < 4; ++i) af1[i] = *(const bf16x8*)(sA + (wm * 64 + i * 16 + l15) * LSTR + 32 + quad * 8);
; #pragma unroll
;         for (int j = 0; j < 4; ++j) bf1[j] = *(const bf16x8*)(sB + (wn * 64 + j * 16 + l15) * LSTR + 32 + quad * 8);
;         __builtin_amdgcn_sched_barrier(0);
;         if (kt + 1 < nk) GEMM_LOAD(ra0, ra1, ra2, ra3, rb0, rb1, rb2, rb3, (kt + 1) * 64)
.LBB0_1559:
	s_barrier
	s_waitcnt vmcnt(7)
	ds_write_b128 v172, v[56:59]
	s_waitcnt vmcnt(6)
	ds_write_b128 v172, v[60:63] offset:5120
	s_waitcnt vmcnt(5)
	ds_write_b128 v172, v[64:67] offset:10240
	s_waitcnt vmcnt(4)
	ds_write_b128 v172, v[72:75] offset:15360
	s_waitcnt vmcnt(3)
	ds_write_b128 v172, v[80:83] offset:20480
	s_waitcnt vmcnt(2)
	ds_write_b128 v172, v[84:87] offset:25600
	s_waitcnt vmcnt(1)
	ds_write_b128 v172, v[88:91] offset:30720
	s_waitcnt vmcnt(0)
	ds_write_b128 v172, v[92:95] offset:35840
	v_add_u32_e32 v96, v174, v175
	s_setprio 1
	s_waitcnt lgkmcnt(0)
	s_barrier
	ds_read_b128 v[156:159], v96
	ds_read_b128 v[152:155], v96 offset:2560
	ds_read_b128 v[132:135], v96 offset:5120
	ds_read_b128 v[124:127], v96 offset:7680
	ds_read_b128 v[136:139], v176 offset:20480
	ds_read_b128 v[140:143], v176 offset:23040
	ds_read_b128 v[144:147], v176 offset:25600
	ds_read_b128 v[148:151], v176 offset:28160
	ds_read_b128 v[128:131], v177 offset:64
	ds_read_b128 v[120:123], v177 offset:2624
	ds_read_b128 v[100:103], v177 offset:5184
	ds_read_b128 v[96:99], v177 offset:7744
	ds_read_b128 v[104:107], v178 offset:20544
	ds_read_b128 v[108:111], v178 offset:23104
	ds_read_b128 v[112:115], v178 offset:25664
	ds_read_b128 v[116:119], v178 offset:28224
	s_cmpk_eq_i32 s6, 0x780
	s_cbranch_scc1 .LBB0_1558
	v_lshl_add_u64 v[64:65], v[168:169], 0, s[6:7]
	v_add_co_u32_e32 v56, vcc, 0x1d00000, v64
	v_lshl_add_u64 v[88:89], v[170:171], 0, s[6:7]
	s_nop 0
	v_addc_co_u32_e32 v57, vcc, 0, v65, vcc
	v_add_co_u32_e32 v60, vcc, 0x1d10000, v64
	s_nop 1
	v_addc_co_u32_e32 v61, vcc, 0, v65, vcc
	v_add_co_u32_e32 v66, vcc, 0x1d20000, v64
	global_load_dwordx4 v[56:59], v[56:57], off offset:128
	s_nop 0
	global_load_dwordx4 v[60:63], v[60:61], off offset:128
	v_addc_co_u32_e32 v67, vcc, 0, v65, vcc
	v_add_co_u32_e32 v72, vcc, 0x1d30000, v64
	s_nop 1
	v_addc_co_u32_e32 v73, vcc, 0, v65, vcc
	v_add_co_u32_e32 v80, vcc, 0x880000, v88
	global_load_dwordx4 v[64:67], v[66:67], off offset:128
	s_nop 0
	global_load_dwordx4 v[72:75], v[72:73], off offset:128
	v_addc_co_u32_e32 v81, vcc, 0, v89, vcc
	v_add_co_u32_e32 v84, vcc, 0x890000, v88
	s_nop 1
	v_addc_co_u32_e32 v85, vcc, 0, v89, vcc
	v_add_co_u32_e32 v90, vcc, 0x8a0000, v88
	global_load_dwordx4 v[80:83], v[80:81], off offset:128
	s_nop 0
	global_load_dwordx4 v[84:87], v[84:85], off offset:128
	v_addc_co_u32_e32 v91, vcc, 0, v89, vcc
	v_add_co_u32_e32 v92, vcc, 0x8b0000, v88
	s_nop 1
	v_addc_co_u32_e32 v93, vcc, 0, v89, vcc
	global_load_dwordx4 v[88:91], v[90:91], off offset:128
	s_nop 0
	global_load_dwordx4 v[92:95], v[92:93], off offset:128
	s_branch .LBB0_1558

; template <bool DEEP, class Epi>
; __device__ __forceinline__ void gemm_phase(const bf16_t* __restrict__ A, int lda, const bf16_t* __restrict__ Wt,
;                                            int K, int ntn, bool lat_only, const Epi& epi, char* smem) {
;     ...
;     for (int kt = 0; kt < nk; ++kt) {
;       __syncthreads();
;       GEMM_STORE(ra0, ra1, ra2, ra3, rb0, rb1, rb2, rb3, 0)
;       __syncthreads();
;       {
;         bf16x8 af0[4], bf0[4], af1[4], bf1[4];
;         __builtin_amdgcn_s_setprio(1);
; #pragma unroll
;         for (int i = 0; i < 4; ++i) af0[i] = *(const bf16x8*)(sA + (wm * 64 + i * 16 + l15) * LSTR + quad * 8);
; #pragma unroll
;         for (int j = 0; j < 4; ++j) bf0[j] = *(const bf16x8*)(sB + (wn * 64 + j * 16 + l15) * LSTR + quad * 8);
; #pragma unroll
;         for (int i = 0; i < 4; ++i) af1[i] = *(const bf16x8*)(sA + (wm * 64 + i * 16 + l15) * LSTR + 32 + quad * 8);
; #pragma unroll
;         for (int j = 0; j < 4; ++j) bf1[j] = *(const bf16x8*)(sB + (wn * 64 + j * 16 + l15) * LSTR + 32 + quad * 8);
;         __builtin_amdgcn_sched_barrier(0);
;         if (kt + 1 < nk) GEMM_LOAD(ra0, ra1, ra2, ra3, rb0, rb1, rb2, rb3, (kt + 1) * 64)
.LBB0_1618:
	s_barrier
	s_waitcnt vmcnt(0)
	ds_write_b128 v168, v[64:67]
	ds_write_b128 v168, v[72:75] offset:5120
	ds_write_b128 v168, v[80:83] offset:10240
	ds_write_b128 v168, v[88:91] offset:15360
	ds_write_b128 v168, v[68:71] offset:20480
	ds_write_b128 v168, v[76:79] offset:25600
	ds_write_b128 v168, v[84:87] offset:30720
	ds_write_b128 v168, v[92:95] offset:35840
	v_add_u32_e32 v96, v170, v172
	s_setprio 1
	s_waitcnt lgkmcnt(0)
	s_barrier
	ds_read_b128 v[156:159], v96
	ds_read_b128 v[152:155], v96 offset:2560
	ds_read_b128 v[132:135], v96 offset:5120
	ds_read_b128 v[124:127], v96 offset:7680
	ds_read_b128 v[136:139], v174 offset:20480
	ds_read_b128 v[140:143], v174 offset:23040
	ds_read_b128 v[144:147], v174 offset:25600
	ds_read_b128 v[148:151], v174 offset:28160
	ds_read_b128 v[128:131], v175 offset:64
	ds_read_b128 v[120:123], v175 offset:2624
	ds_read_b128 v[100:103], v175 offset:5184
	ds_read_b128 v[96:99], v175 offset:7744
	ds_read_b128 v[104:107], v176 offset:20544
	ds_read_b128 v[108:111], v176 offset:23104
	ds_read_b128 v[112:115], v176 offset:25664
	ds_read_b128 v[116:119], v176 offset:28224
	s_cmp_gt_u32 s15, 42
	s_cbranch_scc1 .LBB0_1617
	v_lshl_add_u64 v[68:69], v[164:165], 0, s[0:1]
	v_add_co_u32_e32 v64, vcc, 0x5e00000, v68
	v_lshl_add_u64 v[84:85], v[166:167], 0, s[0:1]
	s_nop 0
	v_addc_co_u32_e32 v65, vcc, 0, v69, vcc
	v_add_co_u32_e32 v70, vcc, 0x5e2c000, v68
	s_nop 1
	v_addc_co_u32_e32 v71, vcc, 0, v69, vcc
	global_load_dwordx4 v[64:67], v[64:65], off offset:128
	s_nop 0
	global_load_dwordx4 v[72:75], v[70:71], off offset:128
	v_add_co_u32_e32 v70, vcc, 0x5e58000, v68
	s_nop 1
	v_addc_co_u32_e32 v71, vcc, 0, v69, vcc
	v_add_co_u32_e32 v68, vcc, 0x5e84000, v68
	s_nop 1
	v_addc_co_u32_e32 v69, vcc, 0, v69, vcc
	global_load_dwordx4 v[80:83], v[70:71], off offset:128
	global_load_dwordx4 v[88:91], v[68:69], off offset:128
	v_add_co_u32_e32 v68, vcc, 0x1380000, v84
	s_nop 1
	v_addc_co_u32_e32 v69, vcc, 0, v85, vcc
	v_add_co_u32_e32 v76, vcc, 0x13ac000, v84
	s_nop 1
	v_addc_co_u32_e32 v77, vcc, 0, v85, vcc
	v_add_co_u32_e32 v86, vcc, 0x13d8000, v84
	global_load_dwordx4 v[68:71], v[68:69], off offset:128
	s_nop 0
	global_load_dwordx4 v[76:79], v[76:77], off offset:128
	v_addc_co_u32_e32 v87, vcc, 0, v85, vcc
	v_add_co_u32_e32 v92, vcc, 0x1404000, v84
	s_nop 1
	v_addc_co_u32_e32 v93, vcc, 0, v85, vcc
	global_load_dwordx4 v[84:87], v[86:87], off offset:128
	s_nop 0
	global_load_dwordx4 v[92:95], v[92:93], off offset:128
	s_branch .LBB0_1617
